# main GEMM: priority raise issued before the phase-opening barrier and drop after the phase-closing barrier, off the MFMA wave's barrier-to-barrier path
# speedup vs baseline: 1.0030x; 1.0013x over previous
.Lkl_first:
	s_add_i32 s87, s86, 2
	s_add_u32 s30, s8, 0x80
	s_addc_u32 s31, s9, 0
	s_add_i32 s88, 16, 0x10000
	s_cmp_eq_u32 s57, s60
	s_cselect_b32 s31, s25, s31
	s_cselect_b32 s30, s24, s30
	v_add_u32_e32 v0, s88, v237
	s_cselect_b32 vcc_hi, s27, s85
	s_cselect_b32 vcc_lo, s26, s84
	s_add_i32 s89, 16, 0x14000
	ds_read_b128 v[132:135], v0
	ds_read_b128 v[136:139], v0 offset:1024
	ds_read_b128 v[152:155], v0 offset:2048
	ds_read_b128 v[156:159], v0 offset:3072
	v_add_u32_e32 v0, s89, v237
	ds_read_b128 v[160:163], v0
	ds_read_b128 v[164:167], v0 offset:1024
	ds_read_b128 v[168:171], v0 offset:2048
	ds_read_b128 v[172:175], v0 offset:3072
	v_lshl_add_u64 v[2:3], s[8:9], 0, v[150:151]
	s_add_i32 m0, s95, 0xc000
	ds_read_b128 v[176:179], v246
	ds_read_b128 v[180:183], v246 offset:1024
	ds_read_b128 v[184:187], v246 offset:2048
	ds_read_b128 v[188:191], v246 offset:3072
	ds_read_b128 v[192:195], v246 offset:4096
	ds_read_b128 v[196:199], v246 offset:5120
	ds_read_b128 v[200:203], v246 offset:6144
	ds_read_b128 v[204:207], v246 offset:7168
	global_load_lds_dwordx4 v[2:3], off
	v_lshl_add_u64 v[2:3], s[8:9], 0, v[148:149]
	s_add_i32 m0, s95, 0xe000
	s_nop 0
	global_load_lds_dwordx4 v[2:3], off
	s_waitcnt vmcnt(8)
	s_waitcnt lgkmcnt(0)
	s_setprio 1
	s_barrier
	v_mfma_f32_16x16x32_bf16 v[128:131], v[132:135], v[176:179], 0
	v_mfma_f32_16x16x32_bf16 v[124:127], v[152:155], v[176:179], 0
	v_mfma_f32_16x16x32_bf16 v[112:115], v[132:135], v[184:187], 0
	v_mfma_f32_16x16x32_bf16 v[108:111], v[152:155], v[184:187], 0
	v_mfma_f32_16x16x32_bf16 v[96:99], v[132:135], v[192:195], 0
	v_mfma_f32_16x16x32_bf16 v[92:95], v[152:155], v[192:195], 0
	v_mfma_f32_16x16x32_bf16 v[80:83], v[132:135], v[200:203], 0
	v_mfma_f32_16x16x32_bf16 v[76:79], v[152:155], v[200:203], 0
	v_mfma_f32_16x16x32_bf16 v[128:131], v[136:139], v[180:183], v[128:131]
	v_mfma_f32_16x16x32_bf16 v[124:127], v[156:159], v[180:183], v[124:127]
	v_mfma_f32_16x16x32_bf16 v[112:115], v[136:139], v[188:191], v[112:115]
	v_mfma_f32_16x16x32_bf16 v[108:111], v[156:159], v[188:191], v[108:111]
	v_mfma_f32_16x16x32_bf16 v[96:99], v[136:139], v[196:199], v[96:99]
	v_mfma_f32_16x16x32_bf16 v[92:95], v[156:159], v[196:199], v[92:95]
	v_mfma_f32_16x16x32_bf16 v[80:83], v[136:139], v[204:207], v[80:83]
	v_mfma_f32_16x16x32_bf16 v[76:79], v[156:159], v[204:207], v[76:79]
	s_setprio 0
	s_setprio 1
	v_mfma_f32_16x16x32_bf16 v[120:123], v[160:163], v[176:179], 0
	v_mfma_f32_16x16x32_bf16 v[116:119], v[168:171], v[176:179], 0
	v_mfma_f32_16x16x32_bf16 v[104:107], v[160:163], v[184:187], 0
	v_mfma_f32_16x16x32_bf16 v[100:103], v[168:171], v[184:187], 0
	v_mfma_f32_16x16x32_bf16 v[88:91], v[160:163], v[192:195], 0
	v_mfma_f32_16x16x32_bf16 v[84:87], v[168:171], v[192:195], 0
	v_mfma_f32_16x16x32_bf16 v[72:75], v[160:163], v[200:203], 0
	v_mfma_f32_16x16x32_bf16 v[68:71], v[168:171], v[200:203], 0
	v_mfma_f32_16x16x32_bf16 v[120:123], v[164:167], v[180:183], v[120:123]
	v_mfma_f32_16x16x32_bf16 v[116:119], v[172:175], v[180:183], v[116:119]
	v_mfma_f32_16x16x32_bf16 v[104:107], v[164:167], v[188:191], v[104:107]
	v_mfma_f32_16x16x32_bf16 v[100:103], v[172:175], v[188:191], v[100:103]
	v_mfma_f32_16x16x32_bf16 v[88:91], v[164:167], v[196:199], v[88:91]
	v_mfma_f32_16x16x32_bf16 v[84:87], v[172:175], v[196:199], v[84:87]
	v_mfma_f32_16x16x32_bf16 v[72:75], v[164:167], v[204:207], v[72:75]
	v_mfma_f32_16x16x32_bf16 v[68:71], v[172:175], v[204:207], v[68:71]
	s_barrier
	s_setprio 0
	s_add_i32 s88, s88, s93
	v_lshl_add_u64 v[208:209], vcc, 0, v[142:143]
	s_mov_b32 m0, s88
	ds_read_b128 v[176:179], v246 offset:16384
	ds_read_b128 v[180:183], v246 offset:17408
	ds_read_b128 v[184:187], v246 offset:18432
	ds_read_b128 v[188:191], v246 offset:19456
	ds_read_b128 v[192:195], v246 offset:20480
	ds_read_b128 v[196:199], v246 offset:21504
	ds_read_b128 v[200:203], v246 offset:22528
	ds_read_b128 v[204:207], v246 offset:23552
	global_load_lds_dwordx4 v[208:209], off
	s_add_i32 m0, s88, 0x2000
	v_lshl_add_u64 v[210:211], vcc, 0, v[144:145]
	s_add_u32 vcc_lo, vcc_lo, s18
	s_addc_u32 vcc_hi, vcc_hi, 0
	s_add_i32 s88, s89, s93
	global_load_lds_dwordx4 v[210:211], off
	v_lshl_add_u64 v[212:213], vcc, 0, v[142:143]
	s_mov_b32 m0, s88
	v_lshl_add_u64 v[214:215], vcc, 0, v[144:145]
	global_load_lds_dwordx4 v[212:213], off
	s_add_i32 m0, s88, 0x2000
	v_lshl_add_u64 v[224:225], s[30:31], 0, v[142:143]
	global_load_lds_dwordx4 v[214:215], off
	s_mov_b32 m0, s95
	v_lshl_add_u64 v[226:227], s[30:31], 0, v[144:145]
	global_load_lds_dwordx4 v[224:225], off
	s_mov_b32 m0, s96
	s_nop 0
	global_load_lds_dwordx4 v[226:227], off
	s_waitcnt vmcnt(8)
	s_waitcnt lgkmcnt(0)
	s_setprio 1
	s_barrier
	v_mfma_f32_16x16x32_bf16 v[64:67], v[132:135], v[176:179], 0
	v_mfma_f32_16x16x32_bf16 v[60:63], v[152:155], v[176:179], 0
	v_mfma_f32_16x16x32_bf16 v[48:51], v[132:135], v[184:187], 0
	v_mfma_f32_16x16x32_bf16 v[44:47], v[152:155], v[184:187], 0
	v_mfma_f32_16x16x32_bf16 v[32:35], v[132:135], v[192:195], 0
	v_mfma_f32_16x16x32_bf16 v[28:31], v[152:155], v[192:195], 0
	v_mfma_f32_16x16x32_bf16 v[16:19], v[132:135], v[200:203], 0
	v_mfma_f32_16x16x32_bf16 v[12:15], v[152:155], v[200:203], 0
	v_mfma_f32_16x16x32_bf16 v[64:67], v[136:139], v[180:183], v[64:67]
	v_mfma_f32_16x16x32_bf16 v[60:63], v[156:159], v[180:183], v[60:63]
	v_mfma_f32_16x16x32_bf16 v[48:51], v[136:139], v[188:191], v[48:51]
	v_mfma_f32_16x16x32_bf16 v[44:47], v[156:159], v[188:191], v[44:47]
	v_mfma_f32_16x16x32_bf16 v[32:35], v[136:139], v[196:199], v[32:35]
	v_mfma_f32_16x16x32_bf16 v[28:31], v[156:159], v[196:199], v[28:31]
	v_mfma_f32_16x16x32_bf16 v[16:19], v[136:139], v[204:207], v[16:19]
	v_mfma_f32_16x16x32_bf16 v[12:15], v[156:159], v[204:207], v[12:15]
	s_setprio 0
	s_setprio 1
	v_mfma_f32_16x16x32_bf16 v[56:59], v[160:163], v[176:179], 0
	v_mfma_f32_16x16x32_bf16 v[52:55], v[168:171], v[176:179], 0
	v_mfma_f32_16x16x32_bf16 v[40:43], v[160:163], v[184:187], 0
	v_mfma_f32_16x16x32_bf16 v[36:39], v[168:171], v[184:187], 0
	v_mfma_f32_16x16x32_bf16 v[24:27], v[160:163], v[192:195], 0
	v_mfma_f32_16x16x32_bf16 v[20:23], v[168:171], v[192:195], 0
	v_mfma_f32_16x16x32_bf16 v[8:11], v[160:163], v[200:203], 0
	v_mfma_f32_16x16x32_bf16 v[2:5], v[168:171], v[200:203], 0
	v_mfma_f32_16x16x32_bf16 v[56:59], v[164:167], v[180:183], v[56:59]
	v_mfma_f32_16x16x32_bf16 v[52:55], v[172:175], v[180:183], v[52:55]
	v_mfma_f32_16x16x32_bf16 v[40:43], v[164:167], v[188:191], v[40:43]
	v_mfma_f32_16x16x32_bf16 v[36:39], v[172:175], v[188:191], v[36:39]
	v_mfma_f32_16x16x32_bf16 v[24:27], v[164:167], v[196:199], v[24:27]
	v_mfma_f32_16x16x32_bf16 v[20:23], v[172:175], v[196:199], v[20:23]
	v_mfma_f32_16x16x32_bf16 v[8:11], v[164:167], v[204:207], v[8:11]
	v_mfma_f32_16x16x32_bf16 v[2:5], v[172:175], v[204:207], v[2:5]
	s_barrier
	s_setprio 0
	s_add_i32 s88, 16, 0x18000
	v_add_u32_e32 v0, s88, v237
	s_add_i32 s89, 16, 0x1c000
	ds_read_b128 v[132:135], v0
	ds_read_b128 v[136:139], v0 offset:1024
	ds_read_b128 v[152:155], v0 offset:2048
	ds_read_b128 v[156:159], v0 offset:3072
	v_add_u32_e32 v0, s89, v237
	ds_read_b128 v[160:163], v0
	ds_read_b128 v[164:167], v0 offset:1024
	ds_read_b128 v[168:171], v0 offset:2048
	ds_read_b128 v[172:175], v0 offset:3072
	s_add_u32 s30, s30, s18
	s_addc_u32 s31, s31, 0
	s_mov_b32 m0, s97
	v_lshl_add_u64 v[6:7], s[30:31], 0, v[142:143]
	ds_read_b128 v[176:179], v246 offset:32768
	ds_read_b128 v[180:183], v246 offset:33792
	ds_read_b128 v[184:187], v246 offset:34816
	ds_read_b128 v[188:191], v246 offset:35840
	ds_read_b128 v[192:195], v246 offset:36864
	ds_read_b128 v[196:199], v246 offset:37888
	ds_read_b128 v[200:203], v246 offset:38912
	ds_read_b128 v[204:207], v246 offset:39936
	global_load_lds_dwordx4 v[6:7], off
	v_lshl_add_u64 v[6:7], s[30:31], 0, v[144:145]
	s_mov_b32 m0, s58
	s_nop 0
	global_load_lds_dwordx4 v[6:7], off
	s_waitcnt vmcnt(8)
	s_waitcnt lgkmcnt(0)
	s_setprio 1
	s_barrier
	v_mfma_f32_16x16x32_bf16 v[128:131], v[132:135], v[176:179], v[128:131]
	v_mfma_f32_16x16x32_bf16 v[124:127], v[152:155], v[176:179], v[124:127]
	v_mfma_f32_16x16x32_bf16 v[112:115], v[132:135], v[184:187], v[112:115]
	v_mfma_f32_16x16x32_bf16 v[108:111], v[152:155], v[184:187], v[108:111]
	v_mfma_f32_16x16x32_bf16 v[96:99], v[132:135], v[192:195], v[96:99]
	v_mfma_f32_16x16x32_bf16 v[92:95], v[152:155], v[192:195], v[92:95]
	v_mfma_f32_16x16x32_bf16 v[80:83], v[132:135], v[200:203], v[80:83]
	v_mfma_f32_16x16x32_bf16 v[76:79], v[152:155], v[200:203], v[76:79]
	v_mfma_f32_16x16x32_bf16 v[128:131], v[136:139], v[180:183], v[128:131]
	v_mfma_f32_16x16x32_bf16 v[124:127], v[156:159], v[180:183], v[124:127]
	v_mfma_f32_16x16x32_bf16 v[112:115], v[136:139], v[188:191], v[112:115]
	v_mfma_f32_16x16x32_bf16 v[108:111], v[156:159], v[188:191], v[108:111]
	v_mfma_f32_16x16x32_bf16 v[96:99], v[136:139], v[196:199], v[96:99]
	v_mfma_f32_16x16x32_bf16 v[92:95], v[156:159], v[196:199], v[92:95]
	v_mfma_f32_16x16x32_bf16 v[80:83], v[136:139], v[204:207], v[80:83]
	v_mfma_f32_16x16x32_bf16 v[76:79], v[156:159], v[204:207], v[76:79]
	s_setprio 0
	s_setprio 1
	v_mfma_f32_16x16x32_bf16 v[120:123], v[160:163], v[176:179], v[120:123]
	v_mfma_f32_16x16x32_bf16 v[116:119], v[168:171], v[176:179], v[116:119]
	v_mfma_f32_16x16x32_bf16 v[104:107], v[160:163], v[184:187], v[104:107]
	v_mfma_f32_16x16x32_bf16 v[100:103], v[168:171], v[184:187], v[100:103]
	v_mfma_f32_16x16x32_bf16 v[88:91], v[160:163], v[192:195], v[88:91]
	v_mfma_f32_16x16x32_bf16 v[84:87], v[168:171], v[192:195], v[84:87]
	v_mfma_f32_16x16x32_bf16 v[72:75], v[160:163], v[200:203], v[72:75]
	v_mfma_f32_16x16x32_bf16 v[68:71], v[168:171], v[200:203], v[68:71]
	v_mfma_f32_16x16x32_bf16 v[120:123], v[164:167], v[180:183], v[120:123]
	v_mfma_f32_16x16x32_bf16 v[116:119], v[172:175], v[180:183], v[116:119]
	v_mfma_f32_16x16x32_bf16 v[104:107], v[164:167], v[188:191], v[104:107]
	v_mfma_f32_16x16x32_bf16 v[100:103], v[172:175], v[188:191], v[100:103]
	v_mfma_f32_16x16x32_bf16 v[88:91], v[164:167], v[196:199], v[88:91]
	v_mfma_f32_16x16x32_bf16 v[84:87], v[172:175], v[196:199], v[84:87]
	v_mfma_f32_16x16x32_bf16 v[72:75], v[164:167], v[204:207], v[72:75]
	v_mfma_f32_16x16x32_bf16 v[68:71], v[172:175], v[204:207], v[68:71]
	s_barrier
	s_setprio 0
	s_add_i32 s30, s88, s93
	v_lshl_add_u64 v[6:7], v[208:209], 0, s[36:37]
	s_mov_b32 m0, s30
	ds_read_b128 v[176:179], v246 offset:49152
	ds_read_b128 v[180:183], v246 offset:50176
	ds_read_b128 v[184:187], v246 offset:51200
	ds_read_b128 v[188:191], v246 offset:52224
	ds_read_b128 v[192:195], v246 offset:53248
	ds_read_b128 v[196:199], v246 offset:54272
	ds_read_b128 v[200:203], v246 offset:55296
	ds_read_b128 v[204:207], v246 offset:56320
	global_load_lds_dwordx4 v[6:7], off
	v_lshl_add_u64 v[6:7], v[210:211], 0, s[36:37]
	s_add_i32 m0, s30, 0x2000
	s_add_i32 s30, s89, s93
	global_load_lds_dwordx4 v[6:7], off
	v_lshl_add_u64 v[6:7], v[212:213], 0, s[36:37]
	s_mov_b32 m0, s30
	s_nop 0
	global_load_lds_dwordx4 v[6:7], off
	v_lshl_add_u64 v[6:7], v[214:215], 0, s[36:37]
	s_add_i32 m0, s30, 0x2000
	s_nop 0
	global_load_lds_dwordx4 v[6:7], off
	v_lshl_add_u64 v[6:7], v[224:225], 0, s[36:37]
	s_mov_b32 m0, s21
	s_nop 0
	global_load_lds_dwordx4 v[6:7], off
	v_lshl_add_u64 v[6:7], v[226:227], 0, s[36:37]
	s_mov_b32 m0, s33
	s_nop 0
	global_load_lds_dwordx4 v[6:7], off
	s_waitcnt vmcnt(8)
	s_waitcnt lgkmcnt(0)
	s_setprio 1
	s_barrier
	v_mfma_f32_16x16x32_bf16 v[64:67], v[132:135], v[176:179], v[64:67]
	v_mfma_f32_16x16x32_bf16 v[60:63], v[152:155], v[176:179], v[60:63]
	v_mfma_f32_16x16x32_bf16 v[48:51], v[132:135], v[184:187], v[48:51]
	v_mfma_f32_16x16x32_bf16 v[44:47], v[152:155], v[184:187], v[44:47]
	v_mfma_f32_16x16x32_bf16 v[32:35], v[132:135], v[192:195], v[32:35]
	v_mfma_f32_16x16x32_bf16 v[28:31], v[152:155], v[192:195], v[28:31]
	v_mfma_f32_16x16x32_bf16 v[16:19], v[132:135], v[200:203], v[16:19]
	v_mfma_f32_16x16x32_bf16 v[12:15], v[152:155], v[200:203], v[12:15]
	v_mfma_f32_16x16x32_bf16 v[64:67], v[136:139], v[180:183], v[64:67]
	v_mfma_f32_16x16x32_bf16 v[60:63], v[156:159], v[180:183], v[60:63]
	v_mfma_f32_16x16x32_bf16 v[48:51], v[136:139], v[188:191], v[48:51]
	v_mfma_f32_16x16x32_bf16 v[44:47], v[156:159], v[188:191], v[44:47]
	v_mfma_f32_16x16x32_bf16 v[32:35], v[136:139], v[196:199], v[32:35]
	v_mfma_f32_16x16x32_bf16 v[28:31], v[156:159], v[196:199], v[28:31]
	v_mfma_f32_16x16x32_bf16 v[16:19], v[136:139], v[204:207], v[16:19]
	v_mfma_f32_16x16x32_bf16 v[12:15], v[156:159], v[204:207], v[12:15]
	s_setprio 0
	s_setprio 1
	v_mfma_f32_16x16x32_bf16 v[56:59], v[160:163], v[176:179], v[56:59]
	v_mfma_f32_16x16x32_bf16 v[52:55], v[168:171], v[176:179], v[52:55]
	v_mfma_f32_16x16x32_bf16 v[40:43], v[160:163], v[184:187], v[40:43]
	v_mfma_f32_16x16x32_bf16 v[36:39], v[168:171], v[184:187], v[36:39]
	v_mfma_f32_16x16x32_bf16 v[24:27], v[160:163], v[192:195], v[24:27]
	v_mfma_f32_16x16x32_bf16 v[20:23], v[168:171], v[192:195], v[20:23]
	v_mfma_f32_16x16x32_bf16 v[6:9], v[160:163], v[200:203], v[8:11]
	v_mfma_f32_16x16x32_bf16 v[2:5], v[168:171], v[200:203], v[2:5]
	v_mfma_f32_16x16x32_bf16 v[56:59], v[164:167], v[180:183], v[56:59]
	v_mfma_f32_16x16x32_bf16 v[52:55], v[172:175], v[180:183], v[52:55]
	v_mfma_f32_16x16x32_bf16 v[40:43], v[164:167], v[188:191], v[40:43]
	v_mfma_f32_16x16x32_bf16 v[36:39], v[172:175], v[188:191], v[36:39]
	v_mfma_f32_16x16x32_bf16 v[24:27], v[164:167], v[196:199], v[24:27]
	v_mfma_f32_16x16x32_bf16 v[20:23], v[172:175], v[196:199], v[20:23]
	v_mfma_f32_16x16x32_bf16 v[8:11], v[164:167], v[204:207], v[6:9]
	v_mfma_f32_16x16x32_bf16 v[4:7], v[172:175], v[204:207], v[2:5]
	s_barrier
	s_setprio 0
	s_andn2_b64 vcc, exec, s[22:23]
	s_cbranch_vccnz .LBB0_1202
	s_branch .Lkl_1200
.LBB0_1199:
	s_add_i32 s87, s86, 2
	s_add_u32 s30, s8, 0x80
	s_addc_u32 s31, s9, 0
	s_add_i32 s88, 16, 0x10000
	s_cmp_eq_u32 s57, s60
	s_cselect_b32 s31, s25, s31
	s_cselect_b32 s30, s24, s30
	v_add_u32_e32 v0, s88, v237
	s_cselect_b32 vcc_hi, s27, s85
	s_cselect_b32 vcc_lo, s26, s84
	s_add_i32 s89, 16, 0x14000
	ds_read_b128 v[132:135], v0
	ds_read_b128 v[136:139], v0 offset:1024
	ds_read_b128 v[152:155], v0 offset:2048
	ds_read_b128 v[156:159], v0 offset:3072
	v_add_u32_e32 v0, s89, v237
	ds_read_b128 v[160:163], v0
	ds_read_b128 v[164:167], v0 offset:1024
	ds_read_b128 v[168:171], v0 offset:2048
	ds_read_b128 v[172:175], v0 offset:3072
	v_lshl_add_u64 v[2:3], s[8:9], 0, v[150:151]
	s_add_i32 m0, s95, 0xc000
	ds_read_b128 v[176:179], v246
	ds_read_b128 v[180:183], v246 offset:1024
	ds_read_b128 v[184:187], v246 offset:2048
	ds_read_b128 v[188:191], v246 offset:3072
	ds_read_b128 v[192:195], v246 offset:4096
	ds_read_b128 v[196:199], v246 offset:5120
	ds_read_b128 v[200:203], v246 offset:6144
	ds_read_b128 v[204:207], v246 offset:7168
	global_load_lds_dwordx4 v[2:3], off
	v_lshl_add_u64 v[2:3], s[8:9], 0, v[148:149]
	s_add_i32 m0, s95, 0xe000
	s_nop 0
	global_load_lds_dwordx4 v[2:3], off
	s_waitcnt vmcnt(8)
	s_waitcnt lgkmcnt(0)
	s_setprio 1
	s_barrier
	v_mfma_f32_16x16x32_bf16 v[128:131], v[132:135], v[176:179], v[128:131]
	v_mfma_f32_16x16x32_bf16 v[124:127], v[152:155], v[176:179], v[124:127]
	v_mfma_f32_16x16x32_bf16 v[112:115], v[132:135], v[184:187], v[112:115]
	v_mfma_f32_16x16x32_bf16 v[108:111], v[152:155], v[184:187], v[108:111]
	v_mfma_f32_16x16x32_bf16 v[96:99], v[132:135], v[192:195], v[96:99]
	v_mfma_f32_16x16x32_bf16 v[92:95], v[152:155], v[192:195], v[92:95]
	v_mfma_f32_16x16x32_bf16 v[80:83], v[132:135], v[200:203], v[80:83]
	v_mfma_f32_16x16x32_bf16 v[76:79], v[152:155], v[200:203], v[76:79]
	v_mfma_f32_16x16x32_bf16 v[128:131], v[136:139], v[180:183], v[128:131]
	v_mfma_f32_16x16x32_bf16 v[124:127], v[156:159], v[180:183], v[124:127]
	v_mfma_f32_16x16x32_bf16 v[112:115], v[136:139], v[188:191], v[112:115]
	v_mfma_f32_16x16x32_bf16 v[108:111], v[156:159], v[188:191], v[108:111]
	v_mfma_f32_16x16x32_bf16 v[96:99], v[136:139], v[196:199], v[96:99]
	v_mfma_f32_16x16x32_bf16 v[92:95], v[156:159], v[196:199], v[92:95]
	v_mfma_f32_16x16x32_bf16 v[80:83], v[136:139], v[204:207], v[80:83]
	v_mfma_f32_16x16x32_bf16 v[76:79], v[156:159], v[204:207], v[76:79]
	s_setprio 0
	s_setprio 1
	v_mfma_f32_16x16x32_bf16 v[120:123], v[160:163], v[176:179], v[120:123]
	v_mfma_f32_16x16x32_bf16 v[116:119], v[168:171], v[176:179], v[116:119]
	v_mfma_f32_16x16x32_bf16 v[104:107], v[160:163], v[184:187], v[104:107]
	v_mfma_f32_16x16x32_bf16 v[100:103], v[168:171], v[184:187], v[100:103]
	v_mfma_f32_16x16x32_bf16 v[88:91], v[160:163], v[192:195], v[88:91]
	v_mfma_f32_16x16x32_bf16 v[84:87], v[168:171], v[192:195], v[84:87]
	v_mfma_f32_16x16x32_bf16 v[72:75], v[160:163], v[200:203], v[72:75]
	v_mfma_f32_16x16x32_bf16 v[68:71], v[168:171], v[200:203], v[68:71]
	v_mfma_f32_16x16x32_bf16 v[120:123], v[164:167], v[180:183], v[120:123]
	v_mfma_f32_16x16x32_bf16 v[116:119], v[172:175], v[180:183], v[116:119]
	v_mfma_f32_16x16x32_bf16 v[104:107], v[164:167], v[188:191], v[104:107]
	v_mfma_f32_16x16x32_bf16 v[100:103], v[172:175], v[188:191], v[100:103]
	v_mfma_f32_16x16x32_bf16 v[88:91], v[164:167], v[196:199], v[88:91]
	v_mfma_f32_16x16x32_bf16 v[84:87], v[172:175], v[196:199], v[84:87]
	v_mfma_f32_16x16x32_bf16 v[72:75], v[164:167], v[204:207], v[72:75]
	v_mfma_f32_16x16x32_bf16 v[68:71], v[172:175], v[204:207], v[68:71]
	s_barrier
	s_setprio 0
	s_add_i32 s88, s88, s93
	v_lshl_add_u64 v[208:209], vcc, 0, v[142:143]
	s_mov_b32 m0, s88
	ds_read_b128 v[176:179], v246 offset:16384
	ds_read_b128 v[180:183], v246 offset:17408
	ds_read_b128 v[184:187], v246 offset:18432
	ds_read_b128 v[188:191], v246 offset:19456
	ds_read_b128 v[192:195], v246 offset:20480
	ds_read_b128 v[196:199], v246 offset:21504
	ds_read_b128 v[200:203], v246 offset:22528
	ds_read_b128 v[204:207], v246 offset:23552
	global_load_lds_dwordx4 v[208:209], off
	s_add_i32 m0, s88, 0x2000
	v_lshl_add_u64 v[210:211], vcc, 0, v[144:145]
	s_add_u32 vcc_lo, vcc_lo, s18
	s_addc_u32 vcc_hi, vcc_hi, 0
	s_add_i32 s88, s89, s93
	global_load_lds_dwordx4 v[210:211], off
	v_lshl_add_u64 v[212:213], vcc, 0, v[142:143]
	s_mov_b32 m0, s88
	v_lshl_add_u64 v[214:215], vcc, 0, v[144:145]
	global_load_lds_dwordx4 v[212:213], off
	s_add_i32 m0, s88, 0x2000
	v_lshl_add_u64 v[224:225], s[30:31], 0, v[142:143]
	global_load_lds_dwordx4 v[214:215], off
	s_mov_b32 m0, s95
	v_lshl_add_u64 v[226:227], s[30:31], 0, v[144:145]
	global_load_lds_dwordx4 v[224:225], off
	s_mov_b32 m0, s96
	s_nop 0
	global_load_lds_dwordx4 v[226:227], off
	s_waitcnt vmcnt(8)
	s_waitcnt lgkmcnt(0)
	s_setprio 1
	s_barrier
	v_mfma_f32_16x16x32_bf16 v[64:67], v[132:135], v[176:179], v[64:67]
	v_mfma_f32_16x16x32_bf16 v[60:63], v[152:155], v[176:179], v[60:63]
	v_mfma_f32_16x16x32_bf16 v[48:51], v[132:135], v[184:187], v[48:51]
	v_mfma_f32_16x16x32_bf16 v[44:47], v[152:155], v[184:187], v[44:47]
	v_mfma_f32_16x16x32_bf16 v[32:35], v[132:135], v[192:195], v[32:35]
	v_mfma_f32_16x16x32_bf16 v[28:31], v[152:155], v[192:195], v[28:31]
	v_mfma_f32_16x16x32_bf16 v[16:19], v[132:135], v[200:203], v[16:19]
	v_mfma_f32_16x16x32_bf16 v[12:15], v[152:155], v[200:203], v[12:15]
	v_mfma_f32_16x16x32_bf16 v[64:67], v[136:139], v[180:183], v[64:67]
	v_mfma_f32_16x16x32_bf16 v[60:63], v[156:159], v[180:183], v[60:63]
	v_mfma_f32_16x16x32_bf16 v[48:51], v[136:139], v[188:191], v[48:51]
	v_mfma_f32_16x16x32_bf16 v[44:47], v[156:159], v[188:191], v[44:47]
	v_mfma_f32_16x16x32_bf16 v[32:35], v[136:139], v[196:199], v[32:35]
	v_mfma_f32_16x16x32_bf16 v[28:31], v[156:159], v[196:199], v[28:31]
	v_mfma_f32_16x16x32_bf16 v[16:19], v[136:139], v[204:207], v[16:19]
	v_mfma_f32_16x16x32_bf16 v[12:15], v[156:159], v[204:207], v[12:15]
	s_setprio 0
	s_setprio 1
	v_mfma_f32_16x16x32_bf16 v[56:59], v[160:163], v[176:179], v[56:59]
	v_mfma_f32_16x16x32_bf16 v[52:55], v[168:171], v[176:179], v[52:55]
	v_mfma_f32_16x16x32_bf16 v[40:43], v[160:163], v[184:187], v[40:43]
	v_mfma_f32_16x16x32_bf16 v[36:39], v[168:171], v[184:187], v[36:39]
	v_mfma_f32_16x16x32_bf16 v[24:27], v[160:163], v[192:195], v[24:27]
	v_mfma_f32_16x16x32_bf16 v[20:23], v[168:171], v[192:195], v[20:23]
	v_mfma_f32_16x16x32_bf16 v[8:11], v[160:163], v[200:203], v[8:11]
	v_mfma_f32_16x16x32_bf16 v[2:5], v[168:171], v[200:203], v[4:7]
	v_mfma_f32_16x16x32_bf16 v[56:59], v[164:167], v[180:183], v[56:59]
	v_mfma_f32_16x16x32_bf16 v[52:55], v[172:175], v[180:183], v[52:55]
	v_mfma_f32_16x16x32_bf16 v[40:43], v[164:167], v[188:191], v[40:43]
	v_mfma_f32_16x16x32_bf16 v[36:39], v[172:175], v[188:191], v[36:39]
	v_mfma_f32_16x16x32_bf16 v[24:27], v[164:167], v[196:199], v[24:27]
	v_mfma_f32_16x16x32_bf16 v[20:23], v[172:175], v[196:199], v[20:23]
	v_mfma_f32_16x16x32_bf16 v[8:11], v[164:167], v[204:207], v[8:11]
	v_mfma_f32_16x16x32_bf16 v[2:5], v[172:175], v[204:207], v[2:5]
	s_barrier
	s_setprio 0
	s_add_i32 s88, 16, 0x18000
	v_add_u32_e32 v0, s88, v237
	s_add_i32 s89, 16, 0x1c000
	ds_read_b128 v[132:135], v0
	ds_read_b128 v[136:139], v0 offset:1024
	ds_read_b128 v[152:155], v0 offset:2048
	ds_read_b128 v[156:159], v0 offset:3072
	v_add_u32_e32 v0, s89, v237
	ds_read_b128 v[160:163], v0
	ds_read_b128 v[164:167], v0 offset:1024
	ds_read_b128 v[168:171], v0 offset:2048
	ds_read_b128 v[172:175], v0 offset:3072
	s_add_u32 s30, s30, s18
	s_addc_u32 s31, s31, 0
	s_mov_b32 m0, s97
	v_lshl_add_u64 v[6:7], s[30:31], 0, v[142:143]
	ds_read_b128 v[176:179], v246 offset:32768
	ds_read_b128 v[180:183], v246 offset:33792
	ds_read_b128 v[184:187], v246 offset:34816
	ds_read_b128 v[188:191], v246 offset:35840
	ds_read_b128 v[192:195], v246 offset:36864
	ds_read_b128 v[196:199], v246 offset:37888
	ds_read_b128 v[200:203], v246 offset:38912
	ds_read_b128 v[204:207], v246 offset:39936
	global_load_lds_dwordx4 v[6:7], off
	v_lshl_add_u64 v[6:7], s[30:31], 0, v[144:145]
	s_mov_b32 m0, s58
	s_nop 0
	global_load_lds_dwordx4 v[6:7], off
	s_waitcnt vmcnt(8)
	s_waitcnt lgkmcnt(0)
	s_setprio 1
	s_barrier
	v_mfma_f32_16x16x32_bf16 v[128:131], v[132:135], v[176:179], v[128:131]
	v_mfma_f32_16x16x32_bf16 v[124:127], v[152:155], v[176:179], v[124:127]
	v_mfma_f32_16x16x32_bf16 v[112:115], v[132:135], v[184:187], v[112:115]
	v_mfma_f32_16x16x32_bf16 v[108:111], v[152:155], v[184:187], v[108:111]
	v_mfma_f32_16x16x32_bf16 v[96:99], v[132:135], v[192:195], v[96:99]
	v_mfma_f32_16x16x32_bf16 v[92:95], v[152:155], v[192:195], v[92:95]
	v_mfma_f32_16x16x32_bf16 v[80:83], v[132:135], v[200:203], v[80:83]
	v_mfma_f32_16x16x32_bf16 v[76:79], v[152:155], v[200:203], v[76:79]
	v_mfma_f32_16x16x32_bf16 v[128:131], v[136:139], v[180:183], v[128:131]
	v_mfma_f32_16x16x32_bf16 v[124:127], v[156:159], v[180:183], v[124:127]
	v_mfma_f32_16x16x32_bf16 v[112:115], v[136:139], v[188:191], v[112:115]
	v_mfma_f32_16x16x32_bf16 v[108:111], v[156:159], v[188:191], v[108:111]
	v_mfma_f32_16x16x32_bf16 v[96:99], v[136:139], v[196:199], v[96:99]
	v_mfma_f32_16x16x32_bf16 v[92:95], v[156:159], v[196:199], v[92:95]
	v_mfma_f32_16x16x32_bf16 v[80:83], v[136:139], v[204:207], v[80:83]
	v_mfma_f32_16x16x32_bf16 v[76:79], v[156:159], v[204:207], v[76:79]
	s_setprio 0
	s_setprio 1
	v_mfma_f32_16x16x32_bf16 v[120:123], v[160:163], v[176:179], v[120:123]
	v_mfma_f32_16x16x32_bf16 v[116:119], v[168:171], v[176:179], v[116:119]
	v_mfma_f32_16x16x32_bf16 v[104:107], v[160:163], v[184:187], v[104:107]
	v_mfma_f32_16x16x32_bf16 v[100:103], v[168:171], v[184:187], v[100:103]
	v_mfma_f32_16x16x32_bf16 v[88:91], v[160:163], v[192:195], v[88:91]
	v_mfma_f32_16x16x32_bf16 v[84:87], v[168:171], v[192:195], v[84:87]
	v_mfma_f32_16x16x32_bf16 v[72:75], v[160:163], v[200:203], v[72:75]
	v_mfma_f32_16x16x32_bf16 v[68:71], v[168:171], v[200:203], v[68:71]
	v_mfma_f32_16x16x32_bf16 v[120:123], v[164:167], v[180:183], v[120:123]
	v_mfma_f32_16x16x32_bf16 v[116:119], v[172:175], v[180:183], v[116:119]
	v_mfma_f32_16x16x32_bf16 v[104:107], v[164:167], v[188:191], v[104:107]
	v_mfma_f32_16x16x32_bf16 v[100:103], v[172:175], v[188:191], v[100:103]
	v_mfma_f32_16x16x32_bf16 v[88:91], v[164:167], v[196:199], v[88:91]
	v_mfma_f32_16x16x32_bf16 v[84:87], v[172:175], v[196:199], v[84:87]
	v_mfma_f32_16x16x32_bf16 v[72:75], v[164:167], v[204:207], v[72:75]
	v_mfma_f32_16x16x32_bf16 v[68:71], v[172:175], v[204:207], v[68:71]
	s_barrier
	s_setprio 0
	s_add_i32 s30, s88, s93
	v_lshl_add_u64 v[6:7], v[208:209], 0, s[36:37]
	s_mov_b32 m0, s30
	ds_read_b128 v[176:179], v246 offset:49152
	ds_read_b128 v[180:183], v246 offset:50176
	ds_read_b128 v[184:187], v246 offset:51200
	ds_read_b128 v[188:191], v246 offset:52224
	ds_read_b128 v[192:195], v246 offset:53248
	ds_read_b128 v[196:199], v246 offset:54272
	ds_read_b128 v[200:203], v246 offset:55296
	ds_read_b128 v[204:207], v246 offset:56320
	global_load_lds_dwordx4 v[6:7], off
	v_lshl_add_u64 v[6:7], v[210:211], 0, s[36:37]
	s_add_i32 m0, s30, 0x2000
	s_add_i32 s30, s89, s93
	global_load_lds_dwordx4 v[6:7], off
	v_lshl_add_u64 v[6:7], v[212:213], 0, s[36:37]
	s_mov_b32 m0, s30
	s_nop 0
	global_load_lds_dwordx4 v[6:7], off
	v_lshl_add_u64 v[6:7], v[214:215], 0, s[36:37]
	s_add_i32 m0, s30, 0x2000
	s_nop 0
	global_load_lds_dwordx4 v[6:7], off
	v_lshl_add_u64 v[6:7], v[224:225], 0, s[36:37]
	s_mov_b32 m0, s21
	s_nop 0
	global_load_lds_dwordx4 v[6:7], off
	v_lshl_add_u64 v[6:7], v[226:227], 0, s[36:37]
	s_mov_b32 m0, s33
	s_nop 0
	global_load_lds_dwordx4 v[6:7], off
	s_waitcnt vmcnt(8)
	s_waitcnt lgkmcnt(0)
	s_setprio 1
	s_barrier
	v_mfma_f32_16x16x32_bf16 v[64:67], v[132:135], v[176:179], v[64:67]
	v_mfma_f32_16x16x32_bf16 v[60:63], v[152:155], v[176:179], v[60:63]
	v_mfma_f32_16x16x32_bf16 v[48:51], v[132:135], v[184:187], v[48:51]
	v_mfma_f32_16x16x32_bf16 v[44:47], v[152:155], v[184:187], v[44:47]
	v_mfma_f32_16x16x32_bf16 v[32:35], v[132:135], v[192:195], v[32:35]
	v_mfma_f32_16x16x32_bf16 v[28:31], v[152:155], v[192:195], v[28:31]
	v_mfma_f32_16x16x32_bf16 v[16:19], v[132:135], v[200:203], v[16:19]
	v_mfma_f32_16x16x32_bf16 v[12:15], v[152:155], v[200:203], v[12:15]
	v_mfma_f32_16x16x32_bf16 v[64:67], v[136:139], v[180:183], v[64:67]
	v_mfma_f32_16x16x32_bf16 v[60:63], v[156:159], v[180:183], v[60:63]
	v_mfma_f32_16x16x32_bf16 v[48:51], v[136:139], v[188:191], v[48:51]
	v_mfma_f32_16x16x32_bf16 v[44:47], v[156:159], v[188:191], v[44:47]
	v_mfma_f32_16x16x32_bf16 v[32:35], v[136:139], v[196:199], v[32:35]
	v_mfma_f32_16x16x32_bf16 v[28:31], v[156:159], v[196:199], v[28:31]
	v_mfma_f32_16x16x32_bf16 v[16:19], v[136:139], v[204:207], v[16:19]
	v_mfma_f32_16x16x32_bf16 v[12:15], v[156:159], v[204:207], v[12:15]
	s_setprio 0
	s_setprio 1
	v_mfma_f32_16x16x32_bf16 v[56:59], v[160:163], v[176:179], v[56:59]
	v_mfma_f32_16x16x32_bf16 v[52:55], v[168:171], v[176:179], v[52:55]
	v_mfma_f32_16x16x32_bf16 v[40:43], v[160:163], v[184:187], v[40:43]
	v_mfma_f32_16x16x32_bf16 v[36:39], v[168:171], v[184:187], v[36:39]
	v_mfma_f32_16x16x32_bf16 v[24:27], v[160:163], v[192:195], v[24:27]
	v_mfma_f32_16x16x32_bf16 v[20:23], v[168:171], v[192:195], v[20:23]
	v_mfma_f32_16x16x32_bf16 v[6:9], v[160:163], v[200:203], v[8:11]
	v_mfma_f32_16x16x32_bf16 v[2:5], v[168:171], v[200:203], v[2:5]
	v_mfma_f32_16x16x32_bf16 v[56:59], v[164:167], v[180:183], v[56:59]
	v_mfma_f32_16x16x32_bf16 v[52:55], v[172:175], v[180:183], v[52:55]
	v_mfma_f32_16x16x32_bf16 v[40:43], v[164:167], v[188:191], v[40:43]
	v_mfma_f32_16x16x32_bf16 v[36:39], v[172:175], v[188:191], v[36:39]
	v_mfma_f32_16x16x32_bf16 v[24:27], v[164:167], v[196:199], v[24:27]
	v_mfma_f32_16x16x32_bf16 v[20:23], v[172:175], v[196:199], v[20:23]
	v_mfma_f32_16x16x32_bf16 v[8:11], v[164:167], v[204:207], v[6:9]
	v_mfma_f32_16x16x32_bf16 v[4:7], v[172:175], v[204:207], v[2:5]
	s_barrier
	s_setprio 0
	s_andn2_b64 vcc, exec, s[22:23]
	s_cbranch_vccnz .LBB0_1202
